# fcum: all 16 forget-gate partial loads issued together (one round trip instead of four)
# baseline (speedup 1.0000x reference)
; __device__ __forceinline__ float softplus_g(float x) { return x > 20.f ? x : log1pf(__expf(x)); }
; __device__ __forceinline__ void p5a_fcum(const Args& A, char* lds, int G) {
;     ...
;     for (int item = blockIdx.x; item < NB * 24; item += G) { const int b = item / 24, h = item % 24; const float fb = A.in[I_OFGB][h];
;         float v[4]; float run = 0.f;
; #pragma unroll
;         for (int i = 0; i < 4; ++i) { const size_t ix = ((size_t)b * SEQL + 4 * tid + i) * 24 + h; const float* L1p = (const float*)(A.ws + WS_LFP);
;             const float fr_ = (LF[ix] + L1p[ix]) + (L1p[ix + (size_t)MROWS * 24] + L1p[ix + (size_t)2 * MROWS * 24]) + fb; run += -softplus_g(-fr_); v[i] = run; }
.LBB0_1310:
	s_mul_hi_i32 s30, s52, 0x2aaaaaab
	s_lshr_b32 s31, s30, 31
	s_ashr_i32 s30, s30, 2
	s_add_i32 s30, s30, s31
	s_mul_i32 s31, s30, 24
	s_sub_i32 s54, s52, s31
	s_ashr_i32 s55, s54, 31
	s_lshl_b64 s[56:57], s[54:55], 2
	s_add_u32 s56, s5, s56
	s_addc_u32 s57, s4, s57
	s_ashr_i32 s31, s30, 31
	s_lshl_b64 s[58:59], s[30:31], 11
	v_lshl_add_u64 v[14:15], s[58:59], 0, v[4:5]
	v_mad_u64_u32 v[0:1], s[58:59], v14, 24, s[54:55]
	v_mad_i32_i24 v1, v15, 24, v1
	v_lshlrev_b64 v[0:1], 2, v[0:1]
	v_lshl_add_u64 v[2:3], s[44:45], 0, v[0:1]
	v_lshl_add_u64 v[0:1], s[46:47], 0, v[0:1]
	v_add_co_u32_e32 v40, vcc, s42, v0
	flat_load_dword v42, v[2:3]
	s_nop 0
	v_addc_co_u32_e32 v41, vcc, 0, v1, vcc
	v_add_co_u32_e32 v46, vcc, 0x300000, v0
	flat_load_dword v44, v[0:1]
	s_nop 0
	v_addc_co_u32_e32 v47, vcc, 0, v1, vcc
	flat_load_dword v43, v[40:41]
	flat_load_dword v45, v[46:47]
	flat_load_dword v168, v[2:3] offset:96
	flat_load_dword v169, v[0:1] offset:96
	flat_load_dword v170, v[40:41] offset:96
	flat_load_dword v171, v[46:47] offset:96
	flat_load_dword v172, v[2:3] offset:192
	flat_load_dword v173, v[0:1] offset:192
	flat_load_dword v174, v[40:41] offset:192
	flat_load_dword v175, v[46:47] offset:192
	flat_load_dword v176, v[2:3] offset:288
	flat_load_dword v177, v[0:1] offset:288
	flat_load_dword v178, v[40:41] offset:288
	flat_load_dword v179, v[46:47] offset:288
	v_mov_b64_e32 v[40:41], s[56:57]
	flat_load_dword v40, v[40:41]
	s_waitcnt vmcnt(0) lgkmcnt(0)
	v_pk_add_f32 v[42:43], v[42:43], v[44:45]
	s_nop 0
	v_add_f32_e32 v11, v42, v43
	v_add_f32_e32 v11, v40, v11
	v_xor_b32_e32 v39, 0x80000000, v11
	v_cmp_ngt_f32_e32 vcc, s43, v11
	s_and_saveexec_b64 s[56:57], vcc
	s_cbranch_execz .LBB0_1312
	v_mul_f32_e32 v11, 0xbfb8aa3b, v11
	v_exp_f32_e32 v39, v11
	s_nop 0
	v_add_f32_e32 v11, 1.0, v39
	v_frexp_mant_f32_e32 v44, v11
	v_cvt_f64_f32_e32 v[42:43], v11
	v_add_f32_e32 v41, -1.0, v11
	v_frexp_exp_i32_f64_e32 v42, v[42:43]
	v_cmp_gt_f32_e32 vcc, s51, v44
	v_sub_f32_e32 v45, v41, v11
	v_sub_f32_e32 v41, v39, v41
	v_subbrev_co_u32_e32 v50, vcc, 0, v42, vcc
	v_add_f32_e32 v45, 1.0, v45
	v_sub_u32_e32 v42, 0, v50
	v_add_f32_e32 v41, v41, v45
	v_ldexp_f32 v11, v11, v42
	v_ldexp_f32 v41, v41, v42
	v_add_f32_e32 v42, -1.0, v11
	v_add_f32_e32 v43, 1.0, v42
	v_sub_f32_e32 v43, v11, v43
	v_add_f32_e32 v44, v41, v43
	v_add_f32_e32 v43, 1.0, v11
	v_add_f32_e32 v45, -1.0, v43
	v_sub_f32_e32 v11, v11, v45
	v_add_f32_e32 v11, v41, v11
	v_add_f32_e32 v41, v43, v11
	v_rcp_f32_e32 v51, v41
	v_sub_f32_e32 v43, v41, v43
	v_sub_f32_e32 v11, v11, v43
	v_add_f32_e32 v43, v42, v44
	v_sub_f32_e32 v42, v43, v42
	v_mul_f32_e32 v53, v43, v51
	v_sub_f32_e32 v52, v44, v42
	v_mul_f32_e32 v44, v41, v53
	v_fma_f32 v46, v53, v41, -v44
	v_fmac_f32_e32 v46, v53, v11
	v_add_f32_e32 v42, v44, v46
	v_sub_f32_e32 v45, v43, v42
	v_pk_add_f32 v[48:49], v[42:43], v[44:45] neg_lo:[0,1] neg_hi:[0,1]
	v_mov_b32_e32 v47, v42
	v_pk_add_f32 v[42:43], v[48:49], v[46:47] neg_lo:[0,1] neg_hi:[0,1]
	v_cmp_neq_f32_e32 vcc, s63, v39
	v_add_f32_e32 v43, v52, v43
	v_add_f32_e32 v42, v42, v43
	v_add_f32_e32 v43, v45, v42
	v_mul_f32_e32 v52, v51, v43
	v_mul_f32_e32 v44, v41, v52
	v_fma_f32 v46, v52, v41, -v44
	v_fmac_f32_e32 v46, v52, v11
	v_sub_f32_e32 v11, v45, v43
	v_add_f32_e32 v11, v42, v11
	v_add_f32_e32 v42, v44, v46
	v_sub_f32_e32 v45, v43, v42
	v_pk_add_f32 v[48:49], v[42:43], v[44:45] neg_lo:[0,1] neg_hi:[0,1]
	v_mov_b32_e32 v47, v42
	v_pk_add_f32 v[42:43], v[48:49], v[46:47] neg_lo:[0,1] neg_hi:[0,1]
	v_add_f32_e32 v41, v53, v52
	v_add_f32_e32 v11, v11, v43
	v_add_f32_e32 v11, v42, v11
	v_add_f32_e32 v11, v45, v11
	v_sub_f32_e32 v42, v41, v53
	v_mul_f32_e32 v11, v51, v11
	v_sub_f32_e32 v42, v52, v42
	v_add_f32_e32 v43, v42, v11
	v_add_f32_e32 v44, v41, v43
	v_cvt_f32_i32_e32 v42, v50
	v_mul_f32_e32 v46, v44, v44
	v_fmamk_f32 v11, v46, 0x3e9b6dac, v34
	v_sub_f32_e32 v41, v44, v41
	v_fmaak_f32 v11, v46, v11, 0x3f2aaada
	v_sub_f32_e32 v41, v43, v41
	v_mul_f32_e32 v43, v44, v46
	v_pk_mul_f32 v[46:47], v[42:43], v[10:11]
	v_ldexp_f32 v45, v44, 1
	v_fma_f32 v44, v42, s62, -v46
	v_fmac_f32_e32 v44, 0xb102e308, v42
	v_pk_add_f32 v[42:43], v[46:47], v[44:45]
	v_ldexp_f32 v41, v41, 1
	v_sub_f32_e32 v11, v43, v45
	v_sub_f32_e32 v11, v47, v11
	v_add_f32_e32 v49, v41, v11
	v_mov_b32_e32 v48, v46
	v_pk_add_f32 v[46:47], v[42:43], v[46:47] neg_lo:[0,1] neg_hi:[0,1]
	v_pk_add_f32 v[50:51], v[42:43], v[48:49]
	v_mov_b32_e32 v45, v42
	v_mov_b32_e32 v47, v51
	v_pk_add_f32 v[52:53], v[44:45], v[46:47] neg_lo:[0,1] neg_hi:[0,1]
	v_pk_add_f32 v[44:45], v[44:45], v[46:47]
	v_mov_b32_e32 v48, v49
	v_pk_add_f32 v[46:47], v[44:45], v[42:43] op_sel:[1,0] op_sel_hi:[0,1] neg_lo:[0,1] neg_hi:[0,1]
	v_pk_add_f32 v[54:55], v[50:51], v[46:47] op_sel_hi:[1,0] neg_lo:[0,1] neg_hi:[0,1]
	v_mov_b32_e32 v50, v51
	v_mov_b32_e32 v51, v45
	v_pk_mov_b32 v[46:47], v[42:43], v[46:47] op_sel:[1,0]
	v_mov_b32_e32 v49, v42
	v_pk_add_f32 v[46:47], v[50:51], v[46:47] neg_lo:[0,1] neg_hi:[0,1]
	v_mov_b32_e32 v54, v52
	v_pk_add_f32 v[42:43], v[48:49], v[46:47] neg_lo:[0,1] neg_hi:[0,1]
	v_mov_b32_e32 v53, v45
	v_pk_add_f32 v[46:47], v[54:55], v[42:43]
	s_nop 0
	v_pk_add_f32 v[48:49], v[46:47], v[46:47] op_sel:[0,1] op_sel_hi:[1,0]
	s_nop 0
	v_pk_add_f32 v[44:45], v[44:45], v[48:49] op_sel:[1,0] op_sel_hi:[0,1]
	v_mov_b32_e32 v47, v44
	v_pk_add_f32 v[50:51], v[46:47], v[52:53] neg_lo:[0,1] neg_hi:[0,1]
	v_mov_b32_e32 v43, v48
	v_sub_f32_e32 v11, v46, v50
	v_pk_add_f32 v[42:43], v[42:43], v[50:51] neg_lo:[0,1] neg_hi:[0,1]
	v_sub_f32_e32 v11, v52, v11
	v_add_f32_e32 v11, v42, v11
	v_add_f32_e32 v11, v11, v43
	v_add_f32_e32 v11, v44, v11
	v_cndmask_b32_e32 v11, v36, v11, vcc
	v_cmp_ngt_f32_e32 vcc, -1.0, v39
	s_nop 1
	v_cndmask_b32_e32 v11, v37, v11, vcc
	v_cmp_neq_f32_e32 vcc, -1.0, v39
	s_nop 1
	v_cndmask_b32_e32 v11, v38, v11, vcc
	v_cmp_lt_f32_e64 vcc, |v39|, s64
	s_nop 1
	v_cndmask_b32_e32 v39, v11, v39, vcc
; __device__ __forceinline__ float softplus_g(float x) { return x > 20.f ? x : log1pf(__expf(x)); }
; __device__ __forceinline__ void p5a_fcum(const Args& A, char* lds, int G) {
;     ...
;         for (int i = 0; i < 4; ++i) { const size_t ix = ((size_t)b * SEQL + 4 * tid + i) * 24 + h; const float* L1p = (const float*)(A.ws + WS_LFP);
;             const float fr_ = (LF[ix] + L1p[ix]) + (L1p[ix + (size_t)MROWS * 24] + L1p[ix + (size_t)2 * MROWS * 24]) + fb; run += -softplus_g(-fr_); v[i] = run; }
.LBB0_1312:
	s_or_b64 exec, exec, s[56:57]
	v_mad_u64_u32 v[42:43], s[56:57], v14, 24, 0
	v_mad_i32_i24 v43, v15, 24, v43
	v_lshl_add_u64 v[14:15], s[54:55], 0, v[42:43]
	v_lshl_add_u64 v[14:15], v[14:15], 2, v[12:13]
	v_lshl_add_u64 v[42:43], s[44:45], 0, v[14:15]
	v_lshl_add_u64 v[14:15], s[46:47], 0, v[14:15]
	v_add_co_u32_e32 v44, vcc, 0x180000, v14
	v_mov_b32_e32 v42, v168
	s_nop 0
	v_addc_co_u32_e32 v45, vcc, 0, v15, vcc
	v_add_co_u32_e32 v46, vcc, 0x300000, v14
	s_nop 1
	v_addc_co_u32_e32 v47, vcc, 0, v15, vcc
	v_mov_b32_e32 v14, v169
	s_nop 0
	v_mov_b32_e32 v43, v170
	v_mov_b32_e32 v15, v171
	s_waitcnt vmcnt(0) lgkmcnt(0)
	v_pk_add_f32 v[14:15], v[42:43], v[14:15]
	s_nop 0
	v_add_f32_e32 v11, v14, v15
	v_add_f32_e32 v11, v40, v11
	v_xor_b32_e32 v14, 0x80000000, v11
	v_cmp_ngt_f32_e32 vcc, s43, v11
	s_and_saveexec_b64 s[56:57], vcc
	s_cbranch_execz .LBB0_1314
	v_mul_f32_e32 v11, 0xbfb8aa3b, v11
	v_exp_f32_e32 v41, v11
	s_nop 0
	v_add_f32_e32 v11, 1.0, v41
	v_frexp_mant_f32_e32 v43, v11
	v_cvt_f64_f32_e32 v[14:15], v11
	v_add_f32_e32 v42, -1.0, v11
	v_frexp_exp_i32_f64_e32 v14, v[14:15]
	v_cmp_gt_f32_e32 vcc, s51, v43
	v_sub_f32_e32 v44, v42, v11
	v_sub_f32_e32 v42, v41, v42
	v_subbrev_co_u32_e32 v48, vcc, 0, v14, vcc
	v_add_f32_e32 v44, 1.0, v44
	v_sub_u32_e32 v14, 0, v48
	v_add_f32_e32 v42, v42, v44
	v_ldexp_f32 v11, v11, v14
	v_ldexp_f32 v14, v42, v14
	v_add_f32_e32 v42, -1.0, v11
	v_add_f32_e32 v15, 1.0, v42
	v_sub_f32_e32 v15, v11, v15
	v_add_f32_e32 v43, v14, v15
	v_add_f32_e32 v15, 1.0, v11
	v_add_f32_e32 v44, -1.0, v15
	v_sub_f32_e32 v11, v11, v44
	v_add_f32_e32 v11, v14, v11
	v_add_f32_e32 v49, v15, v11
	v_rcp_f32_e32 v50, v49
	v_sub_f32_e32 v14, v49, v15
	v_add_f32_e32 v15, v42, v43
	v_sub_f32_e32 v11, v11, v14
	v_mul_f32_e32 v52, v15, v50
	v_sub_f32_e32 v14, v15, v42
	v_mul_f32_e32 v42, v49, v52
	v_fma_f32 v44, v52, v49, -v42
	v_fmac_f32_e32 v44, v52, v11
	v_sub_f32_e32 v51, v43, v14
	v_add_f32_e32 v14, v42, v44
	v_sub_f32_e32 v43, v15, v14
	v_pk_add_f32 v[46:47], v[14:15], v[42:43] neg_lo:[0,1] neg_hi:[0,1]
	v_mov_b32_e32 v45, v14
	v_pk_add_f32 v[14:15], v[46:47], v[44:45] neg_lo:[0,1] neg_hi:[0,1]
	v_cmp_neq_f32_e32 vcc, s63, v41
	v_add_f32_e32 v15, v51, v15
	v_add_f32_e32 v14, v14, v15
	v_add_f32_e32 v15, v43, v14
	v_mul_f32_e32 v51, v50, v15
	v_mul_f32_e32 v42, v49, v51
	v_fma_f32 v44, v51, v49, -v42
	v_fmac_f32_e32 v44, v51, v11
	v_sub_f32_e32 v11, v43, v15
	v_add_f32_e32 v11, v14, v11
	v_add_f32_e32 v14, v42, v44
	v_sub_f32_e32 v43, v15, v14
	v_pk_add_f32 v[46:47], v[14:15], v[42:43] neg_lo:[0,1] neg_hi:[0,1]
	v_mov_b32_e32 v45, v14
	v_pk_add_f32 v[14:15], v[46:47], v[44:45] neg_lo:[0,1] neg_hi:[0,1]
	s_nop 0
	v_add_f32_e32 v11, v11, v15
	v_add_f32_e32 v11, v14, v11
	v_add_f32_e32 v15, v52, v51
	v_add_f32_e32 v11, v43, v11
	v_sub_f32_e32 v14, v15, v52
	v_mul_f32_e32 v11, v50, v11
	v_sub_f32_e32 v14, v51, v14
	v_add_f32_e32 v42, v14, v11
	v_add_f32_e32 v44, v15, v42
	v_cvt_f32_i32_e32 v14, v48
	v_mul_f32_e32 v45, v44, v44
	v_sub_f32_e32 v15, v44, v15
	v_fmamk_f32 v11, v45, 0x3e9b6dac, v34
	v_sub_f32_e32 v15, v42, v15
	v_fmaak_f32 v11, v45, v11, 0x3f2aaada
	v_ldexp_f32 v46, v15, 1
	v_mul_f32_e32 v15, v44, v45
	v_ldexp_f32 v43, v44, 1
	v_pk_mul_f32 v[44:45], v[14:15], v[10:11]
	s_nop 0
	v_fma_f32 v42, v14, s62, -v44
	v_fmac_f32_e32 v42, 0xb102e308, v14
	v_pk_add_f32 v[14:15], v[44:45], v[42:43]
	s_nop 0
	v_sub_f32_e32 v11, v15, v43
	v_sub_f32_e32 v11, v45, v11
	v_add_f32_e32 v47, v46, v11
	v_mov_b32_e32 v46, v44
	v_pk_add_f32 v[44:45], v[14:15], v[44:45] neg_lo:[0,1] neg_hi:[0,1]
	v_pk_add_f32 v[48:49], v[14:15], v[46:47]
	v_mov_b32_e32 v43, v14
	v_mov_b32_e32 v45, v49
	v_pk_add_f32 v[50:51], v[42:43], v[44:45] neg_lo:[0,1] neg_hi:[0,1]
	v_pk_add_f32 v[42:43], v[42:43], v[44:45]
	v_mov_b32_e32 v46, v47
	v_pk_add_f32 v[44:45], v[42:43], v[14:15] op_sel:[1,0] op_sel_hi:[0,1] neg_lo:[0,1] neg_hi:[0,1]
	v_pk_add_f32 v[52:53], v[48:49], v[44:45] op_sel_hi:[1,0] neg_lo:[0,1] neg_hi:[0,1]
	v_mov_b32_e32 v48, v49
	v_mov_b32_e32 v49, v43
	v_pk_mov_b32 v[44:45], v[14:15], v[44:45] op_sel:[1,0]
	v_mov_b32_e32 v47, v14
	v_pk_add_f32 v[44:45], v[48:49], v[44:45] neg_lo:[0,1] neg_hi:[0,1]
	v_mov_b32_e32 v52, v50
	v_pk_add_f32 v[14:15], v[46:47], v[44:45] neg_lo:[0,1] neg_hi:[0,1]
	v_mov_b32_e32 v51, v43
	v_pk_add_f32 v[44:45], v[52:53], v[14:15]
	s_nop 0
	v_pk_add_f32 v[46:47], v[44:45], v[44:45] op_sel:[0,1] op_sel_hi:[1,0]
	s_nop 0
	v_pk_add_f32 v[42:43], v[42:43], v[46:47] op_sel:[1,0] op_sel_hi:[0,1]
	v_mov_b32_e32 v45, v42
	v_pk_add_f32 v[48:49], v[44:45], v[50:51] neg_lo:[0,1] neg_hi:[0,1]
	v_mov_b32_e32 v15, v46
	v_sub_f32_e32 v11, v44, v48
	v_pk_add_f32 v[14:15], v[14:15], v[48:49] neg_lo:[0,1] neg_hi:[0,1]
	v_sub_f32_e32 v11, v50, v11
	v_add_f32_e32 v11, v14, v11
	v_add_f32_e32 v11, v11, v15
	v_add_f32_e32 v11, v42, v11
	v_cndmask_b32_e32 v11, v36, v11, vcc
	v_cmp_ngt_f32_e32 vcc, -1.0, v41
	s_nop 1
	v_cndmask_b32_e32 v11, v37, v11, vcc
	v_cmp_neq_f32_e32 vcc, -1.0, v41
	s_nop 1
	v_cndmask_b32_e32 v11, v38, v11, vcc
	v_cmp_lt_f32_e64 vcc, |v41|, s64
	s_nop 1
	v_cndmask_b32_e32 v14, v11, v41, vcc
; __device__ __forceinline__ float softplus_g(float x) { return x > 20.f ? x : log1pf(__expf(x)); }
; __device__ __forceinline__ void p5a_fcum(const Args& A, char* lds, int G) {
;     ...
;         for (int i = 0; i < 4; ++i) { const size_t ix = ((size_t)b * SEQL + 4 * tid + i) * 24 + h; const float* L1p = (const float*)(A.ws + WS_LFP);
;             const float fr_ = (LF[ix] + L1p[ix]) + (L1p[ix + (size_t)MROWS * 24] + L1p[ix + (size_t)2 * MROWS * 24]) + fb; run += -softplus_g(-fr_); v[i] = run; }
.LBB0_1314:
	s_or_b64 exec, exec, s[56:57]
	v_add_co_u32_e32 v44, vcc, 0x180000, v0
	v_mov_b32_e32 v42, v172
	s_nop 0
	v_addc_co_u32_e32 v45, vcc, 0, v1, vcc
	v_add_co_u32_e32 v46, vcc, 0x300000, v0
	s_nop 1
	v_addc_co_u32_e32 v47, vcc, 0, v1, vcc
	v_mov_b32_e32 v48, v173
	v_mov_b32_e32 v43, v174
	v_mov_b32_e32 v49, v175
	s_waitcnt vmcnt(0) lgkmcnt(0)
	v_pk_add_f32 v[42:43], v[42:43], v[48:49]
	s_nop 0
	v_add_f32_e32 v11, v42, v43
	v_add_f32_e32 v11, v40, v11
	v_xor_b32_e32 v15, 0x80000000, v11
	v_cmp_ngt_f32_e32 vcc, s43, v11
	s_and_saveexec_b64 s[56:57], vcc
	s_cbranch_execz .LBB0_1316
	v_mul_f32_e32 v11, 0xbfb8aa3b, v11
	v_exp_f32_e32 v15, v11
	s_nop 0
	v_add_f32_e32 v11, 1.0, v15
	v_frexp_mant_f32_e32 v44, v11
	v_cvt_f64_f32_e32 v[42:43], v11
	v_add_f32_e32 v41, -1.0, v11
	v_frexp_exp_i32_f64_e32 v42, v[42:43]
	v_cmp_gt_f32_e32 vcc, s51, v44
	v_sub_f32_e32 v45, v41, v11
	v_sub_f32_e32 v41, v15, v41
	v_subbrev_co_u32_e32 v50, vcc, 0, v42, vcc
	v_add_f32_e32 v45, 1.0, v45
	v_sub_u32_e32 v42, 0, v50
	v_add_f32_e32 v41, v41, v45
	v_ldexp_f32 v11, v11, v42
	v_ldexp_f32 v41, v41, v42
	v_add_f32_e32 v42, -1.0, v11
	v_add_f32_e32 v43, 1.0, v42
	v_sub_f32_e32 v43, v11, v43
	v_add_f32_e32 v44, v41, v43
	v_add_f32_e32 v43, 1.0, v11
	v_add_f32_e32 v45, -1.0, v43
	v_sub_f32_e32 v11, v11, v45
	v_add_f32_e32 v11, v41, v11
	v_add_f32_e32 v41, v43, v11
	v_rcp_f32_e32 v51, v41
	v_sub_f32_e32 v43, v41, v43
	v_sub_f32_e32 v11, v11, v43
	v_add_f32_e32 v43, v42, v44
	v_sub_f32_e32 v42, v43, v42
	v_mul_f32_e32 v53, v43, v51
	v_sub_f32_e32 v52, v44, v42
	v_mul_f32_e32 v44, v41, v53
	v_fma_f32 v46, v53, v41, -v44
	v_fmac_f32_e32 v46, v53, v11
	v_add_f32_e32 v42, v44, v46
	v_sub_f32_e32 v45, v43, v42
	v_pk_add_f32 v[48:49], v[42:43], v[44:45] neg_lo:[0,1] neg_hi:[0,1]
	v_mov_b32_e32 v47, v42
	v_pk_add_f32 v[42:43], v[48:49], v[46:47] neg_lo:[0,1] neg_hi:[0,1]
	v_cmp_neq_f32_e32 vcc, s63, v15
	v_add_f32_e32 v43, v52, v43
	v_add_f32_e32 v42, v42, v43
	v_add_f32_e32 v43, v45, v42
	v_mul_f32_e32 v52, v51, v43
	v_mul_f32_e32 v44, v41, v52
	v_fma_f32 v46, v52, v41, -v44
	v_fmac_f32_e32 v46, v52, v11
	v_sub_f32_e32 v11, v45, v43
	v_add_f32_e32 v11, v42, v11
	v_add_f32_e32 v42, v44, v46
	v_sub_f32_e32 v45, v43, v42
	v_pk_add_f32 v[48:49], v[42:43], v[44:45] neg_lo:[0,1] neg_hi:[0,1]
	v_mov_b32_e32 v47, v42
	v_pk_add_f32 v[42:43], v[48:49], v[46:47] neg_lo:[0,1] neg_hi:[0,1]
	v_add_f32_e32 v41, v53, v52
	v_add_f32_e32 v11, v11, v43
	v_add_f32_e32 v11, v42, v11
	v_add_f32_e32 v11, v45, v11
	v_sub_f32_e32 v42, v41, v53
	v_mul_f32_e32 v11, v51, v11
	v_sub_f32_e32 v42, v52, v42
	v_add_f32_e32 v43, v42, v11
	v_add_f32_e32 v44, v41, v43
	v_cvt_f32_i32_e32 v42, v50
	v_mul_f32_e32 v46, v44, v44
	v_fmamk_f32 v11, v46, 0x3e9b6dac, v34
	v_sub_f32_e32 v41, v44, v41
	v_fmaak_f32 v11, v46, v11, 0x3f2aaada
	v_sub_f32_e32 v41, v43, v41
	v_mul_f32_e32 v43, v44, v46
	v_pk_mul_f32 v[46:47], v[42:43], v[10:11]
	v_ldexp_f32 v45, v44, 1
	v_fma_f32 v44, v42, s62, -v46
	v_fmac_f32_e32 v44, 0xb102e308, v42
	v_pk_add_f32 v[42:43], v[46:47], v[44:45]
	v_ldexp_f32 v41, v41, 1
	v_sub_f32_e32 v11, v43, v45
	v_sub_f32_e32 v11, v47, v11
	v_add_f32_e32 v49, v41, v11
	v_mov_b32_e32 v48, v46
	v_pk_add_f32 v[46:47], v[42:43], v[46:47] neg_lo:[0,1] neg_hi:[0,1]
	v_pk_add_f32 v[50:51], v[42:43], v[48:49]
	v_mov_b32_e32 v45, v42
	v_mov_b32_e32 v47, v51
	v_pk_add_f32 v[52:53], v[44:45], v[46:47] neg_lo:[0,1] neg_hi:[0,1]
	v_pk_add_f32 v[44:45], v[44:45], v[46:47]
	v_mov_b32_e32 v48, v49
	v_pk_add_f32 v[46:47], v[44:45], v[42:43] op_sel:[1,0] op_sel_hi:[0,1] neg_lo:[0,1] neg_hi:[0,1]
	v_pk_add_f32 v[54:55], v[50:51], v[46:47] op_sel_hi:[1,0] neg_lo:[0,1] neg_hi:[0,1]
	v_mov_b32_e32 v50, v51
	v_mov_b32_e32 v51, v45
	v_pk_mov_b32 v[46:47], v[42:43], v[46:47] op_sel:[1,0]
	v_mov_b32_e32 v49, v42
	v_pk_add_f32 v[46:47], v[50:51], v[46:47] neg_lo:[0,1] neg_hi:[0,1]
	v_mov_b32_e32 v54, v52
	v_pk_add_f32 v[42:43], v[48:49], v[46:47] neg_lo:[0,1] neg_hi:[0,1]
	v_mov_b32_e32 v53, v45
	v_pk_add_f32 v[46:47], v[54:55], v[42:43]
	s_nop 0
	v_pk_add_f32 v[48:49], v[46:47], v[46:47] op_sel:[0,1] op_sel_hi:[1,0]
	s_nop 0
	v_pk_add_f32 v[44:45], v[44:45], v[48:49] op_sel:[1,0] op_sel_hi:[0,1]
	v_mov_b32_e32 v47, v44
	v_pk_add_f32 v[50:51], v[46:47], v[52:53] neg_lo:[0,1] neg_hi:[0,1]
	v_mov_b32_e32 v43, v48
	v_sub_f32_e32 v11, v46, v50
	v_pk_add_f32 v[42:43], v[42:43], v[50:51] neg_lo:[0,1] neg_hi:[0,1]
	v_sub_f32_e32 v11, v52, v11
	v_add_f32_e32 v11, v42, v11
	v_add_f32_e32 v11, v11, v43
	v_add_f32_e32 v11, v44, v11
	v_cndmask_b32_e32 v11, v36, v11, vcc
	v_cmp_ngt_f32_e32 vcc, -1.0, v15
	s_nop 1
	v_cndmask_b32_e32 v11, v37, v11, vcc
	v_cmp_neq_f32_e32 vcc, -1.0, v15
	s_nop 1
	v_cndmask_b32_e32 v11, v38, v11, vcc
	v_cmp_lt_f32_e64 vcc, |v15|, s64
	s_nop 1
	v_cndmask_b32_e32 v15, v11, v15, vcc
; __device__ __forceinline__ float softplus_g(float x) { return x > 20.f ? x : log1pf(__expf(x)); }
; __device__ __forceinline__ void p5a_fcum(const Args& A, char* lds, int G) {
;     ...
;         for (int i = 0; i < 4; ++i) { const size_t ix = ((size_t)b * SEQL + 4 * tid + i) * 24 + h; const float* L1p = (const float*)(A.ws + WS_LFP);
;             const float fr_ = (LF[ix] + L1p[ix]) + (L1p[ix + (size_t)MROWS * 24] + L1p[ix + (size_t)2 * MROWS * 24]) + fb; run += -softplus_g(-fr_); v[i] = run; }
.LBB0_1316:
	s_or_b64 exec, exec, s[56:57]
	v_add_co_u32_e32 v42, vcc, 0x180000, v0
	v_mov_b32_e32 v2, v176
	s_nop 0
	v_addc_co_u32_e32 v43, vcc, 0, v1, vcc
	v_add_co_u32_e32 v44, vcc, 0x300000, v0
	s_nop 1
	v_addc_co_u32_e32 v45, vcc, 0, v1, vcc
	v_mov_b32_e32 v0, v177
	s_nop 0
	v_mov_b32_e32 v3, v178
	v_mov_b32_e32 v1, v179
	s_waitcnt vmcnt(0) lgkmcnt(0)
	v_pk_add_f32 v[0:1], v[2:3], v[0:1]
	s_nop 0
	v_add_f32_e32 v0, v0, v1
	v_add_f32_e32 v0, v40, v0
	v_xor_b32_e32 v2, 0x80000000, v0
	v_cmp_ngt_f32_e32 vcc, s43, v0
	s_and_saveexec_b64 s[56:57], vcc
	s_cbranch_execz .LBB0_1318
	v_mul_f32_e32 v0, 0xbfb8aa3b, v0
	v_exp_f32_e32 v50, v0
	s_nop 0
	v_add_f32_e32 v2, 1.0, v50
	v_frexp_mant_f32_e32 v11, v2
	v_cvt_f64_f32_e32 v[0:1], v2
	v_frexp_exp_i32_f64_e32 v0, v[0:1]
	v_cmp_gt_f32_e32 vcc, s51, v11
	v_add_f32_e32 v3, -1.0, v2
	v_sub_f32_e32 v40, v3, v2
	v_subbrev_co_u32_e32 v44, vcc, 0, v0, vcc
	v_sub_u32_e32 v0, 0, v44
	v_sub_f32_e32 v3, v50, v3
	v_add_f32_e32 v40, 1.0, v40
	v_ldexp_f32 v1, v2, v0
	v_add_f32_e32 v3, v3, v40
	v_add_f32_e32 v2, -1.0, v1
	v_add_f32_e32 v11, 1.0, v1
	v_ldexp_f32 v0, v3, v0
	v_add_f32_e32 v3, 1.0, v2
	v_add_f32_e32 v40, -1.0, v11
	v_sub_f32_e32 v3, v1, v3
	v_sub_f32_e32 v1, v1, v40
	v_add_f32_e32 v3, v0, v3
	v_add_f32_e32 v0, v0, v1
	v_add_f32_e32 v45, v11, v0
	v_rcp_f32_e32 v46, v45
	v_sub_f32_e32 v1, v45, v11
	v_sub_f32_e32 v11, v0, v1
	v_add_f32_e32 v1, v2, v3
	v_mul_f32_e32 v48, v1, v46
	v_sub_f32_e32 v0, v1, v2
	v_mul_f32_e32 v2, v45, v48
	v_fma_f32 v40, v48, v45, -v2
	v_fmac_f32_e32 v40, v48, v11
	v_sub_f32_e32 v47, v3, v0
	v_add_f32_e32 v0, v2, v40
	v_sub_f32_e32 v3, v1, v0
	v_pk_add_f32 v[42:43], v[0:1], v[2:3] neg_lo:[0,1] neg_hi:[0,1]
	v_mov_b32_e32 v41, v0
	v_pk_add_f32 v[0:1], v[42:43], v[40:41] neg_lo:[0,1] neg_hi:[0,1]
	v_cmp_neq_f32_e32 vcc, s63, v50
	v_add_f32_e32 v1, v47, v1
	v_add_f32_e32 v0, v0, v1
	v_add_f32_e32 v1, v3, v0
	v_mul_f32_e32 v47, v46, v1
	v_mul_f32_e32 v2, v45, v47
	v_fma_f32 v40, v47, v45, -v2
	v_fmac_f32_e32 v40, v47, v11
	v_sub_f32_e32 v3, v3, v1
	v_add_f32_e32 v11, v0, v3
	v_add_f32_e32 v0, v2, v40
	v_sub_f32_e32 v3, v1, v0
	v_pk_add_f32 v[42:43], v[0:1], v[2:3] neg_lo:[0,1] neg_hi:[0,1]
	v_mov_b32_e32 v41, v0
	v_pk_add_f32 v[0:1], v[42:43], v[40:41] neg_lo:[0,1] neg_hi:[0,1]
	s_nop 0
	v_add_f32_e32 v1, v11, v1
	v_add_f32_e32 v0, v0, v1
	v_add_f32_e32 v1, v48, v47
	v_add_f32_e32 v0, v3, v0
	v_sub_f32_e32 v2, v1, v48
	v_mul_f32_e32 v0, v46, v0
	v_sub_f32_e32 v2, v47, v2
	v_add_f32_e32 v2, v2, v0
	v_add_f32_e32 v40, v1, v2
	v_mul_f32_e32 v41, v40, v40
	v_fmamk_f32 v0, v41, 0x3e9b6dac, v34
	v_fmaak_f32 v11, v41, v0, 0x3f2aaada
	v_cvt_f32_i32_e32 v0, v44
	v_sub_f32_e32 v1, v40, v1
	v_sub_f32_e32 v1, v2, v1
	v_ldexp_f32 v42, v1, 1
	v_mul_f32_e32 v1, v40, v41
	v_ldexp_f32 v3, v40, 1
	v_pk_mul_f32 v[40:41], v[0:1], v[10:11]
	s_nop 0
	v_fma_f32 v2, v0, s62, -v40
	v_fmac_f32_e32 v2, 0xb102e308, v0
	v_pk_add_f32 v[0:1], v[40:41], v[2:3]
	s_nop 0
	v_sub_f32_e32 v3, v1, v3
	v_sub_f32_e32 v3, v41, v3
	v_add_f32_e32 v43, v42, v3
	v_mov_b32_e32 v42, v40
	v_pk_add_f32 v[40:41], v[0:1], v[40:41] neg_lo:[0,1] neg_hi:[0,1]
	v_pk_add_f32 v[44:45], v[0:1], v[42:43]
	v_mov_b32_e32 v3, v0
	v_mov_b32_e32 v41, v45
	v_pk_add_f32 v[46:47], v[2:3], v[40:41] neg_lo:[0,1] neg_hi:[0,1]
	v_pk_add_f32 v[2:3], v[2:3], v[40:41]
	v_mov_b32_e32 v42, v43
	v_pk_add_f32 v[40:41], v[2:3], v[0:1] op_sel:[1,0] op_sel_hi:[0,1] neg_lo:[0,1] neg_hi:[0,1]
	v_pk_add_f32 v[48:49], v[44:45], v[40:41] op_sel_hi:[1,0] neg_lo:[0,1] neg_hi:[0,1]
	v_mov_b32_e32 v44, v45
	v_mov_b32_e32 v45, v3
	v_pk_mov_b32 v[40:41], v[0:1], v[40:41] op_sel:[1,0]
	v_mov_b32_e32 v43, v0
	v_pk_add_f32 v[40:41], v[44:45], v[40:41] neg_lo:[0,1] neg_hi:[0,1]
	v_mov_b32_e32 v48, v46
	v_pk_add_f32 v[0:1], v[42:43], v[40:41] neg_lo:[0,1] neg_hi:[0,1]
	v_mov_b32_e32 v47, v3
	v_pk_add_f32 v[40:41], v[48:49], v[0:1]
	s_nop 0
	v_pk_add_f32 v[42:43], v[40:41], v[40:41] op_sel:[0,1] op_sel_hi:[1,0]
	s_nop 0
	v_pk_add_f32 v[2:3], v[2:3], v[42:43] op_sel:[1,0] op_sel_hi:[0,1]
	v_mov_b32_e32 v41, v2
	v_pk_add_f32 v[44:45], v[40:41], v[46:47] neg_lo:[0,1] neg_hi:[0,1]
	v_mov_b32_e32 v1, v42
	v_sub_f32_e32 v3, v40, v44
	v_pk_add_f32 v[0:1], v[0:1], v[44:45] neg_lo:[0,1] neg_hi:[0,1]
	v_sub_f32_e32 v3, v46, v3
	v_add_f32_e32 v0, v0, v3
	v_add_f32_e32 v0, v0, v1
	v_add_f32_e32 v0, v2, v0
	v_cndmask_b32_e32 v0, v36, v0, vcc
	v_cmp_ngt_f32_e32 vcc, -1.0, v50
	s_nop 1
	v_cndmask_b32_e32 v0, v37, v0, vcc
	v_cmp_neq_f32_e32 vcc, -1.0, v50
	s_nop 1
	v_cndmask_b32_e32 v0, v38, v0, vcc
	v_cmp_lt_f32_e64 vcc, |v50|, s64
	s_nop 1
	v_cndmask_b32_e32 v2, v0, v50, vcc
